# P4 LN1 epilogue: x/stats loads of batch k+1 issued before batch k's wait (double-buffered registers, batches 1-5), on v16
# speedup vs baseline: 1.0030x; 1.0018x over previous
.LBB0_786:
	s_lshl_b32 s0, s5, 5
	s_lshl_b32 s2, s4, 8
	s_or_b32 s0, s2, s0
	s_lshl_b32 s22, s10, 8
	v_and_or_b32 v160, v144, 12, s0
	s_add_i32 s1, s22, s39
	v_ashrrev_i32_e32 v161, 31, v160
	v_lshlrev_b64 v[128:129], 2, v[160:161]
	v_or_b32_e32 v168, s1, v172
	v_lshl_add_u64 v[130:131], s[50:51], 0, v[128:129]
	v_lshl_add_u64 v[140:141], s[52:53], 0, v[128:129]
	v_ashrrev_i32_e32 v169, 31, v168
	s_barrier
	global_load_dwordx4 v[132:135], v[130:131], off
	global_load_dwordx4 v[136:139], v[140:141], off
	global_load_dwordx4 v[142:145], v[130:131], off offset:64
	global_load_dwordx4 v[146:149], v[140:141], off offset:64
	global_load_dwordx4 v[150:153], v[130:131], off offset:512
	global_load_dwordx4 v[156:159], v[130:131], off offset:576
	global_load_dwordx4 v[180:183], v[140:141], off offset:512
	global_load_dwordx4 v[184:187], v[140:141], off offset:576
	v_lshlrev_b64 v[130:131], 12, v[168:169]
	v_lshl_add_u64 v[164:165], v[168:169], 3, s[76:77]
	v_lshl_add_u64 v[130:131], s[48:49], 0, v[130:131]
	global_load_dwordx2 v[204:205], v[164:165], off
	v_lshl_add_u64 v[166:167], v[130:131], 0, v[128:129]
	global_load_dwordx4 v[188:191], v[166:167], off nt
	global_load_dwordx4 v[192:195], v[166:167], off offset:64 nt
	global_load_dwordx4 v[196:199], v[166:167], off offset:512 nt
	global_load_dwordx4 v[200:203], v[166:167], off offset:576 nt
	s_mov_b64 s[24:25], 0x10000
	v_lshl_add_u64 v[254:255], v[166:167], 0, s[24:25]
	global_load_dwordx2 v[228:229], v[164:165], off offset:128
	global_load_dwordx4 v[212:215], v[254:255], off nt
	global_load_dwordx4 v[216:219], v[254:255], off offset:64 nt
	global_load_dwordx4 v[220:223], v[254:255], off offset:512 nt
	global_load_dwordx4 v[224:227], v[254:255], off offset:576 nt
	s_mov_b32 s0, 0x3f9837f0
	v_or_b32_e32 v130, 16, v168
	v_ashrrev_i32_e32 v131, 31, v130
	v_lshlrev_b64 v[206:207], 12, v[130:131]
	s_mov_b32 s2, 0xb0000
	s_waitcnt vmcnt(5)
	v_pk_mul_f32 v[140:141], v[136:137], s[0:1] op_sel_hi:[1,0]
	v_pk_mul_f32 v[136:137], v[144:145], s[0:1] op_sel_hi:[1,0]
	v_pk_mul_f32 v[144:145], v[146:147], s[0:1] op_sel_hi:[1,0]
	v_pk_mul_f32 v[146:147], v[152:153], s[0:1] op_sel_hi:[1,0]
	v_pk_mul_f32 v[154:155], v[158:159], s[0:1] op_sel_hi:[1,0]
	v_pk_mul_f32 v[152:153], v[180:181], s[0:1] op_sel_hi:[1,0]
	v_pk_mul_f32 v[130:131], v[134:135], s[0:1] op_sel_hi:[1,0]
	v_pk_mul_f32 v[134:135], v[138:139], s[0:1] op_sel_hi:[1,0]
	v_pk_mul_f32 v[138:139], v[142:143], s[0:1] op_sel_hi:[1,0]
	v_pk_mul_f32 v[142:143], v[148:149], s[0:1] op_sel_hi:[1,0]
	v_sub_f32_e32 v181, v191, v204
	v_sub_f32_e32 v180, v190, v204
	v_pk_mul_f32 v[148:149], v[150:151], s[0:1] op_sel_hi:[1,0]
	v_pk_mul_f32 v[150:151], v[182:183], s[0:1] op_sel_hi:[1,0]
	v_pk_mul_f32 v[158:159], v[186:187], s[0:1] op_sel_hi:[1,0]
	v_pk_mul_f32 v[162:163], v[184:185], s[0:1] op_sel_hi:[1,0]
	v_sub_f32_e32 v183, v189, v204
	v_sub_f32_e32 v182, v188, v204
	v_sub_f32_e32 v185, v195, v204
	v_sub_f32_e32 v184, v194, v204
	v_sub_f32_e32 v187, v193, v204
	v_sub_f32_e32 v186, v192, v204
	v_sub_f32_e32 v189, v199, v204
	v_sub_f32_e32 v188, v198, v204
	v_sub_f32_e32 v191, v197, v204
	v_sub_f32_e32 v190, v196, v204
	v_sub_f32_e32 v193, v203, v204
	v_sub_f32_e32 v192, v202, v204
	v_sub_f32_e32 v195, v201, v204
	v_sub_f32_e32 v194, v200, v204
	v_pk_mul_f32 v[180:181], v[204:205], v[180:181] op_sel:[1,0]
	v_pk_mul_f32 v[132:133], v[132:133], s[0:1] op_sel_hi:[1,0]
	v_pk_mul_f32 v[156:157], v[156:157], s[0:1] op_sel_hi:[1,0]
	v_pk_mul_f32 v[182:183], v[204:205], v[182:183] op_sel:[1,0]
	v_pk_mul_f32 v[186:187], v[204:205], v[186:187] op_sel:[1,0]
	v_pk_mul_f32 v[184:185], v[204:205], v[184:185] op_sel:[1,0]
	v_pk_mul_f32 v[190:191], v[204:205], v[190:191] op_sel:[1,0]
	v_pk_mul_f32 v[188:189], v[204:205], v[188:189] op_sel:[1,0]
	v_pk_mul_f32 v[194:195], v[204:205], v[194:195] op_sel:[1,0]
	v_pk_mul_f32 v[192:193], v[204:205], v[192:193] op_sel:[1,0]
	v_pk_fma_f32 v[180:181], v[130:131], v[180:181], v[134:135]
	v_pk_fma_f32 v[182:183], v[132:133], v[182:183], v[140:141]
	v_pk_fma_f32 v[184:185], v[136:137], v[184:185], v[142:143]
	v_pk_fma_f32 v[186:187], v[138:139], v[186:187], v[144:145]
	v_pk_fma_f32 v[188:189], v[146:147], v[188:189], v[150:151]
	v_pk_fma_f32 v[190:191], v[148:149], v[190:191], v[152:153]
	v_pk_fma_f32 v[192:193], v[154:155], v[192:193], v[158:159]
	v_pk_fma_f32 v[194:195], v[156:157], v[194:195], v[162:163]
	v_pk_add_f32 v[102:103], v[102:103], v[180:181]
	v_lshl_add_u64 v[180:181], s[48:49], 0, v[206:207]
	v_pk_add_f32 v[100:101], v[100:101], v[182:183]
	v_pk_add_f32 v[98:99], v[98:99], v[184:185]
	v_pk_add_f32 v[96:97], v[96:97], v[186:187]
	v_pk_add_f32 v[78:79], v[78:79], v[188:189]
	v_pk_add_f32 v[76:77], v[76:77], v[190:191]
	v_pk_add_f32 v[70:71], v[70:71], v[192:193]
	v_pk_add_f32 v[68:69], v[68:69], v[194:195]
	v_lshl_add_u64 v[192:193], v[180:181], 0, v[128:129]
	s_mov_b64 s[24:25], 0x20000
	v_lshl_add_u64 v[254:255], v[166:167], 0, s[24:25]
	global_load_dwordx2 v[196:197], v[164:165], off offset:256
	global_load_dwordx4 v[180:183], v[254:255], off nt
	global_load_dwordx4 v[184:187], v[254:255], off offset:64 nt
	global_load_dwordx4 v[188:191], v[254:255], off offset:512 nt
	global_load_dwordx4 v[192:195], v[254:255], off offset:576 nt
	s_nop 0
	v_or_b32_e32 v198, 32, v168
	v_ashrrev_i32_e32 v199, 31, v198
	v_lshlrev_b64 v[198:199], 12, v[198:199]
	v_lshl_add_u64 v[198:199], s[48:49], 0, v[198:199]
	v_lshl_add_u64 v[198:199], v[198:199], 0, v[128:129]
	v_or_b32_e32 v168, 48, v168
	v_ashrrev_i32_e32 v169, 31, v168
	v_lshlrev_b64 v[168:169], 12, v[168:169]
	v_lshl_add_u64 v[168:169], s[48:49], 0, v[168:169]
	v_lshl_add_u64 v[168:169], v[168:169], 0, v[128:129]
	s_mov_b32 s0, 0x80000
	v_mov_b32_e32 v200, v101
	v_mov_b32_e32 v201, v102
	v_mov_b32_e32 v202, v100
	v_mov_b32_e32 v203, v103
	v_mov_b32_e32 v204, v97
	v_mov_b32_e32 v205, v98
	v_pk_add_f32 v[200:201], v[200:201], v[202:203]
	v_mov_b32_e32 v208, v71
	s_waitcnt vmcnt(8)
	v_sub_f32_e32 v215, v215, v228
	v_sub_f32_e32 v214, v214, v228
	v_sub_f32_e32 v213, v213, v228
	v_sub_f32_e32 v212, v212, v228
	s_waitcnt vmcnt(7)
	v_sub_f32_e32 v219, v219, v228
	v_sub_f32_e32 v218, v218, v228
	v_sub_f32_e32 v217, v217, v228
	v_sub_f32_e32 v216, v216, v228
	s_waitcnt vmcnt(6)
	v_sub_f32_e32 v223, v223, v228
	v_sub_f32_e32 v222, v222, v228
	v_sub_f32_e32 v221, v221, v228
	v_sub_f32_e32 v220, v220, v228
	s_waitcnt vmcnt(5)
	v_sub_f32_e32 v227, v227, v228
	v_sub_f32_e32 v226, v226, v228
	v_sub_f32_e32 v225, v225, v228
	v_sub_f32_e32 v224, v224, v228
	v_pk_mul_f32 v[212:213], v[228:229], v[212:213] op_sel:[1,0]
	v_pk_mul_f32 v[214:215], v[228:229], v[214:215] op_sel:[1,0]
	v_pk_mul_f32 v[216:217], v[228:229], v[216:217] op_sel:[1,0]
	v_pk_mul_f32 v[218:219], v[228:229], v[218:219] op_sel:[1,0]
	v_pk_mul_f32 v[220:221], v[228:229], v[220:221] op_sel:[1,0]
	v_pk_mul_f32 v[222:223], v[228:229], v[222:223] op_sel:[1,0]
	v_pk_mul_f32 v[224:225], v[228:229], v[224:225] op_sel:[1,0]
	v_pk_mul_f32 v[226:227], v[228:229], v[226:227] op_sel:[1,0]
	v_pk_fma_f32 v[214:215], v[130:131], v[214:215], v[134:135]
	v_pk_fma_f32 v[212:213], v[132:133], v[212:213], v[140:141]
	v_pk_fma_f32 v[218:219], v[136:137], v[218:219], v[142:143]
	v_pk_fma_f32 v[216:217], v[138:139], v[216:217], v[144:145]
	v_pk_fma_f32 v[222:223], v[146:147], v[222:223], v[150:151]
	v_pk_fma_f32 v[220:221], v[148:149], v[220:221], v[152:153]
	v_pk_fma_f32 v[226:227], v[154:155], v[226:227], v[158:159]
	v_pk_fma_f32 v[224:225], v[156:157], v[224:225], v[162:163]
	v_pk_add_f32 v[110:111], v[110:111], v[214:215]
	v_pk_add_f32 v[108:109], v[108:109], v[212:213]
	v_pk_add_f32 v[86:87], v[86:87], v[218:219]
	v_pk_add_f32 v[84:85], v[84:85], v[216:217]
	v_pk_add_f32 v[74:75], v[74:75], v[222:223]
	v_pk_add_f32 v[72:73], v[72:73], v[220:221]
	v_pk_add_f32 v[66:67], v[66:67], v[226:227]
	v_pk_add_f32 v[64:65], v[64:65], v[224:225]
	s_nop 0
	s_mov_b64 s[24:25], 0x30000
	v_lshl_add_u64 v[254:255], v[166:167], 0, s[24:25]
	global_load_dwordx2 v[228:229], v[164:165], off offset:384
	global_load_dwordx4 v[212:215], v[254:255], off nt
	global_load_dwordx4 v[216:219], v[254:255], off offset:64 nt
	global_load_dwordx4 v[220:223], v[254:255], off offset:512 nt
	global_load_dwordx4 v[224:227], v[254:255], off offset:576 nt
	s_waitcnt vmcnt(8)
	v_sub_f32_e32 v183, v183, v196
	v_sub_f32_e32 v182, v182, v196
	v_sub_f32_e32 v181, v181, v196
	v_sub_f32_e32 v180, v180, v196
	s_waitcnt vmcnt(7)
	v_sub_f32_e32 v187, v187, v196
	v_sub_f32_e32 v186, v186, v196
	v_sub_f32_e32 v185, v185, v196
	v_sub_f32_e32 v184, v184, v196
	s_waitcnt vmcnt(6)
	v_sub_f32_e32 v191, v191, v196
	v_sub_f32_e32 v190, v190, v196
	v_sub_f32_e32 v189, v189, v196
	v_sub_f32_e32 v188, v188, v196
	s_waitcnt vmcnt(5)
	v_sub_f32_e32 v195, v195, v196
	v_sub_f32_e32 v194, v194, v196
	v_sub_f32_e32 v193, v193, v196
	v_sub_f32_e32 v192, v192, v196
	v_pk_mul_f32 v[180:181], v[196:197], v[180:181] op_sel:[1,0]
	v_pk_mul_f32 v[182:183], v[196:197], v[182:183] op_sel:[1,0]
	v_pk_mul_f32 v[184:185], v[196:197], v[184:185] op_sel:[1,0]
	v_pk_mul_f32 v[186:187], v[196:197], v[186:187] op_sel:[1,0]
	v_pk_mul_f32 v[188:189], v[196:197], v[188:189] op_sel:[1,0]
	v_pk_mul_f32 v[190:191], v[196:197], v[190:191] op_sel:[1,0]
	v_pk_mul_f32 v[192:193], v[196:197], v[192:193] op_sel:[1,0]
	v_pk_mul_f32 v[194:195], v[196:197], v[194:195] op_sel:[1,0]
	v_pk_fma_f32 v[182:183], v[130:131], v[182:183], v[134:135]
	v_pk_fma_f32 v[180:181], v[132:133], v[180:181], v[140:141]
	v_pk_fma_f32 v[186:187], v[136:137], v[186:187], v[142:143]
	v_pk_fma_f32 v[184:185], v[138:139], v[184:185], v[144:145]
	v_pk_fma_f32 v[190:191], v[146:147], v[190:191], v[150:151]
	v_pk_fma_f32 v[188:189], v[148:149], v[188:189], v[152:153]
	v_pk_fma_f32 v[194:195], v[154:155], v[194:195], v[158:159]
	v_pk_fma_f32 v[192:193], v[156:157], v[192:193], v[162:163]
	v_pk_add_f32 v[118:119], v[118:119], v[182:183]
	v_pk_add_f32 v[116:117], v[116:117], v[180:181]
	v_pk_add_f32 v[114:115], v[114:115], v[186:187]
	v_pk_add_f32 v[112:113], v[112:113], v[184:185]
	v_pk_add_f32 v[90:91], v[90:91], v[190:191]
	v_pk_add_f32 v[88:89], v[88:89], v[188:189]
	v_pk_add_f32 v[82:83], v[82:83], v[194:195]
	v_pk_add_f32 v[80:81], v[80:81], v[192:193]
	s_nop 0
	s_mov_b64 s[24:25], 0x80000
	v_lshl_add_u64 v[254:255], v[166:167], 0, s[24:25]
	global_load_dwordx2 v[196:197], v[164:165], off offset:1024
	global_load_dwordx4 v[180:183], v[254:255], off nt
	global_load_dwordx4 v[184:187], v[254:255], off offset:64 nt
	global_load_dwordx4 v[188:191], v[254:255], off offset:512 nt
	global_load_dwordx4 v[192:195], v[254:255], off offset:576 nt
	v_add_co_u32_e32 v168, vcc, s0, v166
	s_mov_b64 s[0:1], 0x80000
	s_nop 0
	v_addc_co_u32_e32 v169, vcc, 0, v167, vcc
	s_waitcnt vmcnt(8)
	v_sub_f32_e32 v215, v215, v228
	v_sub_f32_e32 v214, v214, v228
	v_sub_f32_e32 v213, v213, v228
	v_sub_f32_e32 v212, v212, v228
	s_waitcnt vmcnt(7)
	v_sub_f32_e32 v219, v219, v228
	v_sub_f32_e32 v218, v218, v228
	v_sub_f32_e32 v217, v217, v228
	v_sub_f32_e32 v216, v216, v228
	s_waitcnt vmcnt(6)
	v_sub_f32_e32 v223, v223, v228
	v_sub_f32_e32 v222, v222, v228
	v_sub_f32_e32 v221, v221, v228
	v_sub_f32_e32 v220, v220, v228
	s_waitcnt vmcnt(5)
	v_sub_f32_e32 v227, v227, v228
	v_sub_f32_e32 v226, v226, v228
	v_sub_f32_e32 v225, v225, v228
	v_sub_f32_e32 v224, v224, v228
	v_pk_mul_f32 v[212:213], v[228:229], v[212:213] op_sel:[1,0]
	v_pk_mul_f32 v[214:215], v[228:229], v[214:215] op_sel:[1,0]
	v_pk_mul_f32 v[216:217], v[228:229], v[216:217] op_sel:[1,0]
	v_pk_mul_f32 v[218:219], v[228:229], v[218:219] op_sel:[1,0]
	v_pk_mul_f32 v[220:221], v[228:229], v[220:221] op_sel:[1,0]
	v_pk_mul_f32 v[222:223], v[228:229], v[222:223] op_sel:[1,0]
	v_pk_mul_f32 v[224:225], v[228:229], v[224:225] op_sel:[1,0]
	v_pk_mul_f32 v[226:227], v[228:229], v[226:227] op_sel:[1,0]
	v_pk_fma_f32 v[214:215], v[130:131], v[214:215], v[134:135]
	v_pk_fma_f32 v[212:213], v[132:133], v[212:213], v[140:141]
	v_pk_fma_f32 v[218:219], v[136:137], v[218:219], v[142:143]
	v_pk_fma_f32 v[216:217], v[138:139], v[216:217], v[144:145]
	v_pk_fma_f32 v[222:223], v[146:147], v[222:223], v[150:151]
	v_pk_fma_f32 v[220:221], v[148:149], v[220:221], v[152:153]
	v_pk_fma_f32 v[226:227], v[154:155], v[226:227], v[158:159]
	v_pk_fma_f32 v[224:225], v[156:157], v[224:225], v[162:163]
	v_pk_add_f32 v[126:127], v[126:127], v[214:215]
	v_pk_add_f32 v[124:125], v[124:125], v[212:213]
	v_pk_add_f32 v[122:123], v[122:123], v[218:219]
	v_pk_add_f32 v[120:121], v[120:121], v[216:217]
	v_pk_add_f32 v[106:107], v[106:107], v[222:223]
	v_pk_add_f32 v[104:105], v[104:105], v[220:221]
	v_pk_add_f32 v[94:95], v[94:95], v[226:227]
	v_pk_add_f32 v[92:93], v[92:93], v[224:225]
	s_nop 0
	s_mov_b64 s[24:25], 0x90000
	v_lshl_add_u64 v[254:255], v[166:167], 0, s[24:25]
	global_load_dwordx2 v[228:229], v[164:165], off offset:1152
	global_load_dwordx4 v[212:215], v[254:255], off nt
	global_load_dwordx4 v[216:219], v[254:255], off offset:64 nt
	global_load_dwordx4 v[220:223], v[254:255], off offset:512 nt
	global_load_dwordx4 v[224:227], v[254:255], off offset:576 nt
	v_lshl_add_u64 v[168:169], v[166:167], 0, s[0:1]
	s_mov_b32 s0, 0x90000
	v_add_co_u32_e32 v168, vcc, s0, v166
	s_mov_b64 s[0:1], 0x90000
	s_nop 0
	v_addc_co_u32_e32 v169, vcc, 0, v167, vcc
	s_waitcnt vmcnt(8)
	v_sub_f32_e32 v181, v181, v196
	v_sub_f32_e32 v180, v180, v196
	v_sub_f32_e32 v183, v183, v196
	v_sub_f32_e32 v182, v182, v196
	s_waitcnt vmcnt(7)
	v_sub_f32_e32 v187, v187, v196
	v_sub_f32_e32 v186, v186, v196
	v_sub_f32_e32 v185, v185, v196
	v_sub_f32_e32 v184, v184, v196
	s_waitcnt vmcnt(6)
	v_sub_f32_e32 v191, v191, v196
	v_sub_f32_e32 v190, v190, v196
	v_sub_f32_e32 v189, v189, v196
	v_sub_f32_e32 v188, v188, v196
	s_waitcnt vmcnt(5)
	v_sub_f32_e32 v195, v195, v196
	v_sub_f32_e32 v194, v194, v196
	v_sub_f32_e32 v193, v193, v196
	v_sub_f32_e32 v192, v192, v196
	v_pk_mul_f32 v[182:183], v[196:197], v[182:183] op_sel:[1,0]
	v_pk_mul_f32 v[180:181], v[196:197], v[180:181] op_sel:[1,0]
	v_pk_mul_f32 v[184:185], v[196:197], v[184:185] op_sel:[1,0]
	v_pk_mul_f32 v[186:187], v[196:197], v[186:187] op_sel:[1,0]
	v_pk_mul_f32 v[188:189], v[196:197], v[188:189] op_sel:[1,0]
	v_pk_mul_f32 v[190:191], v[196:197], v[190:191] op_sel:[1,0]
	v_pk_mul_f32 v[192:193], v[196:197], v[192:193] op_sel:[1,0]
	v_pk_mul_f32 v[194:195], v[196:197], v[194:195] op_sel:[1,0]
	v_pk_fma_f32 v[180:181], v[132:133], v[180:181], v[140:141]
	v_pk_fma_f32 v[182:183], v[130:131], v[182:183], v[134:135]
	v_pk_fma_f32 v[186:187], v[136:137], v[186:187], v[142:143]
	v_pk_fma_f32 v[184:185], v[138:139], v[184:185], v[144:145]
	v_pk_fma_f32 v[190:191], v[146:147], v[190:191], v[150:151]
	v_pk_fma_f32 v[188:189], v[148:149], v[188:189], v[152:153]
	v_pk_fma_f32 v[194:195], v[154:155], v[194:195], v[158:159]
	v_pk_fma_f32 v[192:193], v[156:157], v[192:193], v[162:163]
	v_pk_add_f32 v[62:63], v[62:63], v[182:183]
	v_pk_add_f32 v[60:61], v[60:61], v[180:181]
	v_pk_add_f32 v[58:59], v[58:59], v[186:187]
	v_pk_add_f32 v[56:57], v[56:57], v[184:185]
	v_pk_add_f32 v[54:55], v[54:55], v[190:191]
	v_pk_add_f32 v[52:53], v[52:53], v[188:189]
	v_pk_add_f32 v[50:51], v[50:51], v[194:195]
	v_pk_add_f32 v[48:49], v[48:49], v[192:193]
	s_nop 0
	v_lshl_add_u64 v[168:169], v[166:167], 0, s[0:1]
	s_mov_b32 s0, 0xa0000
	v_add_co_u32_e32 v198, vcc, s0, v166
	s_mov_b64 s[0:1], 0xa0000
	s_nop 0
	v_addc_co_u32_e32 v199, vcc, 0, v167, vcc
	s_waitcnt vmcnt(3)
	v_sub_f32_e32 v169, v213, v228
	v_sub_f32_e32 v168, v212, v228
	v_sub_f32_e32 v213, v215, v228
	v_sub_f32_e32 v212, v214, v228
	s_waitcnt vmcnt(2)
	v_sub_f32_e32 v215, v219, v228
	v_sub_f32_e32 v214, v218, v228
	v_sub_f32_e32 v217, v217, v228
	v_sub_f32_e32 v216, v216, v228
	s_waitcnt vmcnt(1)
	v_sub_f32_e32 v219, v223, v228
	v_sub_f32_e32 v218, v222, v228
	v_sub_f32_e32 v221, v221, v228
	v_sub_f32_e32 v220, v220, v228
	s_waitcnt vmcnt(0)
	v_sub_f32_e32 v223, v227, v228
	v_sub_f32_e32 v222, v226, v228
	v_sub_f32_e32 v225, v225, v228
	v_sub_f32_e32 v224, v224, v228
	v_pk_mul_f32 v[212:213], v[228:229], v[212:213] op_sel:[1,0]
	v_pk_mul_f32 v[168:169], v[228:229], v[168:169] op_sel:[1,0]
	v_pk_mul_f32 v[216:217], v[228:229], v[216:217] op_sel:[1,0]
	v_pk_mul_f32 v[214:215], v[228:229], v[214:215] op_sel:[1,0]
	v_pk_mul_f32 v[220:221], v[228:229], v[220:221] op_sel:[1,0]
	v_pk_mul_f32 v[218:219], v[228:229], v[218:219] op_sel:[1,0]
	v_pk_mul_f32 v[224:225], v[228:229], v[224:225] op_sel:[1,0]
	v_pk_mul_f32 v[222:223], v[228:229], v[222:223] op_sel:[1,0]
	v_pk_fma_f32 v[168:169], v[132:133], v[168:169], v[140:141]
	v_pk_fma_f32 v[212:213], v[130:131], v[212:213], v[134:135]
	v_pk_fma_f32 v[214:215], v[136:137], v[214:215], v[142:143]
	v_pk_fma_f32 v[216:217], v[138:139], v[216:217], v[144:145]
	v_pk_fma_f32 v[218:219], v[146:147], v[218:219], v[150:151]
	v_pk_fma_f32 v[220:221], v[148:149], v[220:221], v[152:153]
	v_pk_fma_f32 v[222:223], v[154:155], v[222:223], v[158:159]
	v_pk_fma_f32 v[224:225], v[156:157], v[224:225], v[162:163]
	v_pk_add_f32 v[46:47], v[46:47], v[212:213]
	v_pk_add_f32 v[44:45], v[44:45], v[168:169]
	v_pk_add_f32 v[42:43], v[42:43], v[214:215]
	v_pk_add_f32 v[40:41], v[40:41], v[216:217]
	v_pk_add_f32 v[38:39], v[38:39], v[218:219]
	v_pk_add_f32 v[36:37], v[36:37], v[220:221]
	v_pk_add_f32 v[34:35], v[34:35], v[222:223]
	v_pk_add_f32 v[32:33], v[32:33], v[224:225]
	v_lshl_add_u64 v[180:181], v[166:167], 0, s[0:1]
	global_load_dwordx2 v[168:169], v[164:165], off offset:1280
	global_load_dwordx4 v[182:185], v[198:199], off nt
	global_load_dwordx4 v[186:189], v[180:181], off offset:64 nt
	global_load_dwordx4 v[190:193], v[180:181], off offset:512 nt
	global_load_dwordx4 v[194:197], v[180:181], off offset:576 nt
	v_mbcnt_lo_u32_b32 v180, -1, 0
	v_mbcnt_hi_u32_b32 v181, -1, v180
	v_and_b32_e32 v198, 64, v181
	v_xor_b32_e32 v180, 16, v181
	v_add_u32_e32 v210, 64, v198
	s_mov_b64 s[0:1], 0xb0000
	v_cmp_lt_i32_e32 vcc, v180, v210
	v_lshl_add_u64 v[198:199], v[166:167], 0, s[0:1]
	s_lshl_b32 s0, s5, 3
	v_cndmask_b32_e32 v180, v181, v180, vcc
	v_add_co_u32_e32 v166, vcc, s2, v166
	v_lshlrev_b32_e32 v180, 2, v180
	s_nop 0
	v_addc_co_u32_e32 v167, vcc, 0, v167, vcc
	s_add_i32 s2, s0, 0
	s_waitcnt vmcnt(2)
	v_sub_f32_e32 v189, v189, v168
	v_sub_f32_e32 v183, v183, v168
	v_sub_f32_e32 v182, v182, v168
	v_sub_f32_e32 v185, v185, v168
	v_sub_f32_e32 v184, v184, v168
	v_sub_f32_e32 v188, v188, v168
	v_sub_f32_e32 v187, v187, v168
	v_sub_f32_e32 v186, v186, v168
	s_waitcnt vmcnt(1)
	v_sub_f32_e32 v193, v193, v168
	v_sub_f32_e32 v192, v192, v168
	v_sub_f32_e32 v191, v191, v168
	v_sub_f32_e32 v190, v190, v168
	s_waitcnt vmcnt(0)
	v_sub_f32_e32 v197, v197, v168
	v_sub_f32_e32 v196, v196, v168
	v_sub_f32_e32 v195, v195, v168
	v_sub_f32_e32 v194, v194, v168
	v_pk_mul_f32 v[184:185], v[168:169], v[184:185] op_sel:[1,0]
	v_pk_mul_f32 v[182:183], v[168:169], v[182:183] op_sel:[1,0]
	v_pk_mul_f32 v[186:187], v[168:169], v[186:187] op_sel:[1,0]
	v_pk_mul_f32 v[188:189], v[168:169], v[188:189] op_sel:[1,0]
	v_pk_mul_f32 v[190:191], v[168:169], v[190:191] op_sel:[1,0]
	v_pk_mul_f32 v[192:193], v[168:169], v[192:193] op_sel:[1,0]
	v_pk_mul_f32 v[194:195], v[168:169], v[194:195] op_sel:[1,0]
	v_pk_mul_f32 v[168:169], v[168:169], v[196:197] op_sel:[1,0]
	v_pk_fma_f32 v[182:183], v[132:133], v[182:183], v[140:141]
	v_pk_fma_f32 v[184:185], v[130:131], v[184:185], v[134:135]
	v_pk_fma_f32 v[188:189], v[136:137], v[188:189], v[142:143]
	v_pk_fma_f32 v[186:187], v[138:139], v[186:187], v[144:145]
	v_pk_fma_f32 v[192:193], v[146:147], v[192:193], v[150:151]
	v_pk_fma_f32 v[190:191], v[148:149], v[190:191], v[152:153]
	v_pk_fma_f32 v[168:169], v[154:155], v[168:169], v[158:159]
	v_pk_fma_f32 v[194:195], v[156:157], v[194:195], v[162:163]
	v_pk_add_f32 v[30:31], v[30:31], v[184:185]
	v_pk_add_f32 v[28:29], v[28:29], v[182:183]
	v_pk_add_f32 v[26:27], v[26:27], v[188:189]
	v_pk_add_f32 v[24:25], v[24:25], v[186:187]
	v_pk_add_f32 v[22:23], v[22:23], v[192:193]
	v_pk_add_f32 v[20:21], v[20:21], v[190:191]
	v_pk_add_f32 v[18:19], v[18:19], v[168:169]
	v_pk_add_f32 v[16:17], v[16:17], v[194:195]
	v_add_f32_e32 v169, v78, v79
	global_load_dwordx2 v[206:207], v[164:165], off offset:1408
	global_load_dwordx4 v[182:185], v[166:167], off nt
	global_load_dwordx4 v[186:189], v[198:199], off offset:64 nt
	global_load_dwordx4 v[190:193], v[198:199], off offset:512 nt
	global_load_dwordx4 v[194:197], v[198:199], off offset:576 nt
	v_mov_b32_e32 v164, v96
	v_mov_b32_e32 v165, v99
	v_add_f32_e32 v167, v76, v77
	v_mov_b32_e32 v166, v68
	v_mov_b32_e32 v168, v69
	v_pk_add_f32 v[164:165], v[204:205], v[164:165]
	v_pk_add_f32 v[166:167], v[166:167], v[168:169]
	v_add_f32_e32 v168, v200, v201
	v_pk_add_f32 v[164:165], v[164:165], v[164:165] op_sel_hi:[0,1]
	v_add_f32_e32 v209, 0, v168
	v_mov_b32_e32 v164, v70
	v_pk_add_f32 v[164:165], v[164:165], v[208:209]
	s_waitcnt vmcnt(3)
	v_sub_f32_e32 v183, v183, v206
	v_pk_add_f32 v[164:165], v[166:167], v[164:165]
	v_sub_f32_e32 v182, v182, v206
	v_add_f32_e32 v165, v164, v165
	ds_bpermute_b32 v166, v180, v165
	v_xor_b32_e32 v164, 32, v181
	v_cmp_lt_i32_e32 vcc, v164, v210
	v_sub_f32_e32 v185, v185, v206
	v_sub_f32_e32 v184, v184, v206
	v_cndmask_b32_e32 v164, v181, v164, vcc
	v_lshlrev_b32_e32 v164, 2, v164
	s_waitcnt lgkmcnt(0)
	v_add_f32_e32 v165, v165, v166
	ds_bpermute_b32 v166, v164, v165
	s_waitcnt vmcnt(2)
	v_sub_f32_e32 v189, v189, v206
	v_sub_f32_e32 v188, v188, v206
	v_sub_f32_e32 v187, v187, v206
	v_sub_f32_e32 v186, v186, v206
	s_waitcnt lgkmcnt(0)
	v_add_f32_e32 v166, v165, v166
	v_fmamk_f32 v167, v166, 0xbc800000, v103
	v_fmamk_f32 v169, v166, 0xbc800000, v101
	v_fmamk_f32 v198, v166, 0xbc800000, v99
	v_fmamk_f32 v200, v166, 0xbc800000, v97
	v_fmamk_f32 v165, v166, 0xbc800000, v102
	v_fmamk_f32 v168, v166, 0xbc800000, v100
	v_fmamk_f32 v181, v166, 0xbc800000, v98
	v_fmamk_f32 v199, v166, 0xbc800000, v96
	v_fmamk_f32 v202, v166, 0xbc800000, v79
	v_fmamk_f32 v204, v166, 0xbc800000, v77
	v_mul_f32_e32 v169, v169, v169
	v_mul_f32_e32 v167, v167, v167
	v_mul_f32_e32 v200, v200, v200
	v_mul_f32_e32 v198, v198, v198
	v_fmamk_f32 v201, v166, 0xbc800000, v78
	v_fmamk_f32 v203, v166, 0xbc800000, v76
	v_fmamk_f32 v208, v166, 0xbc800000, v71
	v_fmamk_f32 v210, v166, 0xbc800000, v69
	v_mul_f32_e32 v204, v204, v204
	v_mul_f32_e32 v202, v202, v202
	v_fmac_f32_e32 v169, v168, v168
	v_fmac_f32_e32 v167, v165, v165
	v_fmac_f32_e32 v200, v199, v199
	v_fmac_f32_e32 v198, v181, v181
	v_fmamk_f32 v205, v166, 0xbc800000, v70
	v_fmamk_f32 v209, v166, 0xbc800000, v68
	v_mul_f32_e32 v210, v210, v210
	v_mul_f32_e32 v208, v208, v208
	v_fmac_f32_e32 v204, v203, v203
	v_fmac_f32_e32 v202, v201, v201
	v_add_f32_e32 v165, v169, v167
	v_add_f32_e32 v167, v200, v198
	v_fmac_f32_e32 v210, v209, v209
	v_fmac_f32_e32 v208, v205, v205
	v_add_f32_e32 v168, v204, v202
	v_add_f32_e32 v165, v165, v167
	v_add_f32_e32 v169, v210, v208
	v_add_f32_e32 v165, v168, v165
	v_add_f32_e32 v167, v169, v165
	ds_bpermute_b32 v168, v180, v167
	s_waitcnt vmcnt(1)
	v_sub_f32_e32 v193, v193, v206
	v_sub_f32_e32 v192, v192, v206
	v_sub_f32_e32 v191, v191, v206
	v_sub_f32_e32 v190, v190, v206
	s_waitcnt vmcnt(0)
	v_sub_f32_e32 v197, v197, v206
	v_sub_f32_e32 v196, v196, v206
	v_sub_f32_e32 v195, v195, v206
	v_sub_f32_e32 v194, v194, v206
	s_waitcnt lgkmcnt(0)
	v_add_f32_e32 v167, v167, v168
	v_pk_mul_f32 v[184:185], v[206:207], v[184:185] op_sel:[1,0]
	v_pk_mul_f32 v[182:183], v[206:207], v[182:183] op_sel:[1,0]
	v_pk_mul_f32 v[186:187], v[206:207], v[186:187] op_sel:[1,0]
	v_pk_mul_f32 v[188:189], v[206:207], v[188:189] op_sel:[1,0]
	v_pk_mul_f32 v[190:191], v[206:207], v[190:191] op_sel:[1,0]
	v_pk_mul_f32 v[192:193], v[206:207], v[192:193] op_sel:[1,0]
	v_pk_mul_f32 v[194:195], v[206:207], v[194:195] op_sel:[1,0]
	v_pk_mul_f32 v[196:197], v[206:207], v[196:197] op_sel:[1,0]
	ds_bpermute_b32 v168, v164, v167
	v_pk_fma_f32 v[132:133], v[132:133], v[182:183], v[140:141]
	v_pk_fma_f32 v[130:131], v[130:131], v[184:185], v[134:135]
	v_pk_fma_f32 v[134:135], v[136:137], v[188:189], v[142:143]
	v_pk_fma_f32 v[136:137], v[138:139], v[186:187], v[144:145]
	v_pk_fma_f32 v[138:139], v[146:147], v[192:193], v[150:151]
	v_pk_fma_f32 v[140:141], v[148:149], v[190:191], v[152:153]
	v_pk_fma_f32 v[142:143], v[154:155], v[196:197], v[158:159]
	v_pk_fma_f32 v[144:145], v[156:157], v[194:195], v[162:163]
	v_pk_add_f32 v[14:15], v[14:15], v[130:131]
	v_pk_add_f32 v[12:13], v[12:13], v[132:133]
	v_pk_add_f32 v[10:11], v[10:11], v[134:135]
	v_pk_add_f32 v[8:9], v[8:9], v[136:137]
	v_pk_add_f32 v[6:7], v[6:7], v[138:139]
	v_pk_add_f32 v[4:5], v[4:5], v[140:141]
	v_pk_add_f32 v[2:3], v[2:3], v[142:143]
	v_pk_add_f32 v[0:1], v[0:1], v[144:145]
	v_cmp_gt_u32_e32 vcc, 16, v170
	v_lshlrev_b32_e32 v165, 5, v172
	s_and_saveexec_b64 s[0:1], vcc
	s_cbranch_execz .LBB0_788
	s_lshl_b32 s3, s34, 11
	s_add_i32 s3, s2, s3
	v_mul_f32_e32 v130, 0x3c800000, v166
	v_add_u32_e32 v132, s3, v165
	s_waitcnt lgkmcnt(0)
	v_add_f32_e32 v131, v167, v168
	ds_write_b64 v132, v[130:131]
